# v65 + the grid barrier between layer 0's gate phase and layer 1's projection completed XCD-locally (no L2 write-back / cross-XCC hop) in XCD-local mode
# baseline (speedup 1.0000x reference)
; __device__ __forceinline__ unsigned xb_ld(unsigned* p)              { return __hip_atomic_load(p, __ATOMIC_RELAXED, __HIP_MEMORY_SCOPE_AGENT); }
; __device__ __forceinline__ unsigned xb_add(unsigned* p, unsigned v) { return __hip_atomic_fetch_add(p, v, __ATOMIC_RELAXED, __HIP_MEMORY_SCOPE_AGENT); }
; #define XB_SPIN(cond, bar) do { unsigned _sp = 0; while (cond) { __builtin_amdgcn_s_sleep(1); \
;     if ((++_sp & 255u) == 0u) { if (xb_ld(&(bar)[XB_TMO])) break; if (_sp > XB_SPIN_CAP) { atomicAdd(&(bar)[XB_TMO], 1u); break; } } } } while (0)
; __device__ __forceinline__ void xcd_barrier(const XcdBarrier& b, bool local = false) {
;     ...
;         const unsigned old = xb_add(&bar[XB_XSUB(b.x)], 1u);
;         const unsigned gen = old / nloc;
;         if (old + 1u == (gen + 1u) * nloc) {
;             if (!local) {
;             __builtin_amdgcn_fence(__ATOMIC_RELEASE, "agent");
;             asm volatile("s_waitcnt vmcnt(0)" ::: "memory");
;             const unsigned og = xb_add(&bar[XB_TOP], 1u);
;             const unsigned tg = og / nx;
;             if (og + 1u == (tg + 1u) * nx) xb_add(&bar[XB_TOPGEN], 1u);
;             else XB_SPIN(xb_ld(&bar[XB_TOPGEN]) == tg, bar);
;             }
.LBB0_856:
	s_andn2_saveexec_b64 s[4:5], s[4:5]
	s_cbranch_execz .LBB0_876
	s_and_b64 vcc, exec, s[76:77]
	s_cbranch_vccz .Ls6_glob
	s_cmp_eq_u32 s78, 0
	s_cbranch_scc1 .Ls6_loc
.Ls6_glob:
	s_mov_b64 s[4:5], exec
	buffer_wbl2 sc1
	s_waitcnt lgkmcnt(0)
	s_waitcnt vmcnt(0)
	v_mbcnt_lo_u32_b32 v1, s4, 0
	v_mbcnt_hi_u32_b32 v1, s5, v1
	v_cmp_eq_u32_e32 vcc, 0, v1
	s_and_saveexec_b64 s[6:7], vcc
	s_cbranch_execz .LBB0_859
	s_bcnt1_i32_b64 s4, s[4:5]
	v_mov_b32_e32 v3, s4
	v_readlane_b32 s4, v253, 63
	v_readlane_b32 s5, v251, 0
	s_nop 4
	global_atomic_add v3, v0, v3, s[4:5] sc0

; __device__ __forceinline__ unsigned xb_add(unsigned* p, unsigned v) { return __hip_atomic_fetch_add(p, v, __ATOMIC_RELAXED, __HIP_MEMORY_SCOPE_AGENT); }
; __device__ __forceinline__ void xcd_barrier(const XcdBarrier& b, bool local = false) {
;     ...
;             __builtin_amdgcn_fence(__ATOMIC_ACQUIRE, "agent");
;             xb_add(&bar[XB_XGEN(b.x)], 1u);
;             asm volatile("s_waitcnt vmcnt(0)" ::: "memory");
.Ls6_loc:
	s_mov_b64 s[4:5], exec
	v_mbcnt_lo_u32_b32 v1, s4, 0
	v_mbcnt_hi_u32_b32 v1, s5, v1
	v_cmp_eq_u32_e32 vcc, 0, v1
	s_waitcnt vmcnt(0)
	buffer_inv sc1
	s_and_saveexec_b64 s[6:7], vcc
	s_cbranch_execz .LBB0_875
	s_bcnt1_i32_b64 s4, s[4:5]
	v_mov_b32_e32 v1, s4
	v_readlane_b32 s4, v253, 61
	v_readlane_b32 s5, v253, 62
	s_nop 4
	global_atomic_add v0, v1, s[4:5]
